# v87: v76 + FoX K-fragment reads batched ahead of their MFMAs
# baseline (speedup 1.0000x reference)
; #define LAS __attribute__((address_space(3)))
; #define MFMA32(a, b, c) __builtin_amdgcn_mfma_f32_32x32x16_bf16((a), (b), (c), 0, 0, 0)
; template <int MODE>
; __device__ __forceinline__ void attn_unit(const Params& P, LAS unsigned char* lds, const int b, const int h, const int qb) {
;     ...
; #pragma unroll
;             for (int ks = 0; ks < NQ; ++ks) {
;                 const unsigned chunk = mp * 8 + 2 * ks + hh;
;                 const unsigned off = kra + ((chunk ^ kswz) << 4);
;                 const bf16x8 a0 = *(const LAS bf16x8*)(Kb + off), a1 = *(const LAS bf16x8*)(Kb + off + 8192);
;                 s[0] = MFMA32(a0, Qf[ks], s[0]); s[1] = MFMA32(a1, Qf[ks], s[1]);
;             }
;             v_issue<0>(va, vaddr);
;             }
;             if (FOX) {
;                 const LAS float* cl = (const LAS float*)(lds + AL_CLS + (cur * 8 + w) * 256) + 8 * hh;
; #pragma unroll
;                 for (int blk = 0; blk < 2; ++blk)
; #pragma unroll
;                     for (int j4 = 0; j4 < 4; ++j4) { const f32x4 c = *(const LAS f32x4*)(cl + 32 * blk + 16 * (j4 >> 1) + 4 * (j4 & 1));
; #pragma unroll
;                         for (int e = 0; e < 4; ++e) s[blk][4 * j4 + e] -= c[e]; }
.Lfox_nochk:
	s_and_b32 s8, s67, 3
	s_lshl_b32 s9, s8, 15
	s_addk_i32 s9, 0x100
	v_add_u32_e32 v0, s9, v192
	v_add3_u32 v0, v0, v195, v193
	v_add3_u32 v206, v0, v190, s73
	v_add_u32_e32 v0, s9, v194
	v_add_u32_e32 v207, v0, v197
	v_add_u32_e32 v228, v0, v198
	v_add_u32_e32 v229, v0, v199
	v_add_u32_e32 v248, v0, v200
	ds_read_b128 v[2:5], v207
	ds_read_b128 v[6:9], v207 offset:8192
	ds_read_b128 v[10:13], v228
	ds_read_b128 v[80:83], v228 offset:8192
	ds_read_b128 v[84:87], v229
	ds_read_b128 v[88:91], v229 offset:8192
	ds_read_b128 v[92:95], v248
	ds_read_b128 v[162:165], v248 offset:8192
	v_add_u32_e32 v207, v0, v201
	v_add_u32_e32 v249, v0, v202
	ds_read_b128 v[236:239], v207
	ds_read_b128 v[240:243], v207 offset:8192
	ds_read_b128 v[244:247], v249
	ds_read_b128 v[208:211], v249 offset:8192
	v_add_u32_e32 v228, v0, v203
	v_add_u32_e32 v229, v0, v204
	v_lshl_add_u32 v0, s8, 11, v196
	s_cmp_le_i32 s38, s0
	s_waitcnt lgkmcnt(4)
	v_mfma_f32_32x32x16_bf16 v[114:129], v[2:5], v[130:133], v[212:227]
	v_mfma_f32_32x32x16_bf16 v[98:113], v[6:9], v[130:133], v[212:227]
	v_mfma_f32_32x32x16_bf16 v[114:129], v[10:13], v[134:137], v[114:129]
	v_mfma_f32_32x32x16_bf16 v[98:113], v[80:83], v[134:137], v[98:113]
	v_mfma_f32_32x32x16_bf16 v[114:129], v[84:87], v[138:141], v[114:129]
	v_mfma_f32_32x32x16_bf16 v[98:113], v[88:91], v[138:141], v[98:113]
	v_mfma_f32_32x32x16_bf16 v[114:129], v[92:95], v[142:145], v[114:129]
	v_mfma_f32_32x32x16_bf16 v[98:113], v[162:165], v[142:145], v[98:113]
	ds_read_b128 v[2:5], v228
	ds_read_b128 v[6:9], v228 offset:8192
	ds_read_b128 v[10:13], v229
	ds_read_b128 v[80:83], v229 offset:8192
	ds_read_b64_tr_b16 v[174:175], v206 offset:0
	ds_read_b64_tr_b16 v[176:177], v206 offset:0x100
	ds_read_b64_tr_b16 v[170:171], v206 offset:0x200
	ds_read_b64_tr_b16 v[172:173], v206 offset:0x300
	ds_read_b64_tr_b16 v[166:167], v206 offset:0x400
	ds_read_b64_tr_b16 v[168:169], v206 offset:0x500
	ds_read_b64_tr_b16 v[162:163], v206 offset:0x600
	ds_read_b64_tr_b16 v[164:165], v206 offset:0x700
	s_waitcnt lgkmcnt(12)
	v_mfma_f32_32x32x16_bf16 v[114:129], v[236:239], v[146:149], v[114:129]
	v_mfma_f32_32x32x16_bf16 v[98:113], v[240:243], v[146:149], v[98:113]
	v_mfma_f32_32x32x16_bf16 v[114:129], v[244:247], v[150:153], v[114:129]
	v_mfma_f32_32x32x16_bf16 v[98:113], v[208:211], v[150:153], v[98:113]
	s_waitcnt lgkmcnt(8)
	v_mfma_f32_32x32x16_bf16 v[114:129], v[2:5], v[154:157], v[114:129]
	v_mfma_f32_32x32x16_bf16 v[98:113], v[6:9], v[154:157], v[98:113]
	v_mfma_f32_32x32x16_bf16 v[114:129], v[10:13], v[158:161], v[114:129]
	v_mfma_f32_32x32x16_bf16 v[98:113], v[80:83], v[158:161], v[98:113]
	ds_read_b128 v[2:5], v0
	ds_read_b128 v[6:9], v0 offset:16
	ds_read_b128 v[10:13], v0 offset:64
	ds_read_b128 v[82:85], v0 offset:80
	s_waitcnt lgkmcnt(0)
	s_nop 5
	v_sub_f32_e32 v95, v117, v5
	v_sub_f32_e32 v91, v121, v9
	v_sub_f32_e32 v87, v123, v11
	v_sub_f32_e32 v81, v129, v85
	v_sub_f32_e32 v80, v128, v84
	v_sub_f32_e32 v85, v125, v13
	v_sub_f32_e32 v84, v124, v12
	v_sub_f32_e32 v86, v122, v10
	v_sub_f32_e32 v88, v120, v8
	v_sub_f32_e32 v93, v119, v7
	v_sub_f32_e32 v90, v118, v6
	v_sub_f32_e32 v92, v116, v4
	v_sub_f32_e32 v97, v115, v3
	v_sub_f32_e32 v94, v114, v2
	ds_read_b128 v[114:117], v0 offset:128
	ds_read_b128 v[2:5], v0 offset:144
	ds_read_b128 v[6:9], v0 offset:192
	ds_read_b128 v[10:13], v0 offset:208
	v_sub_f32_e32 v83, v127, v83
	v_sub_f32_e32 v82, v126, v82
	s_waitcnt lgkmcnt(0)
	v_sub_f32_e32 v89, v99, v115
	v_sub_f32_e32 v0, v98, v114
	v_sub_f32_e32 v15, v113, v13
	v_sub_f32_e32 v14, v112, v12
	v_sub_f32_e32 v13, v111, v11
	v_sub_f32_e32 v12, v110, v10
	v_sub_f32_e32 v11, v109, v9
	v_sub_f32_e32 v10, v108, v8
	v_sub_f32_e32 v9, v107, v7
	v_sub_f32_e32 v8, v106, v6
	v_sub_f32_e32 v7, v105, v5
	v_sub_f32_e32 v6, v104, v4
	v_sub_f32_e32 v5, v103, v3
	v_sub_f32_e32 v4, v102, v2
	v_sub_f32_e32 v3, v101, v117
	v_sub_f32_e32 v2, v100, v116
	s_cbranch_scc1 .LBB0_458
; template <int MODE>
; __device__ __forceinline__ void attn_unit(const Params& P, LAS unsigned char* lds, const int b, const int h, const int qb) {
;     ...
;             if (kt * 64 + 63 > q0w) {
; #pragma unroll
;                 for (int blk = 0; blk < 2; ++blk)
; #pragma unroll
;                     for (int i = 0; i < 16; ++i) { if (kbase + 32 * blk + 16 * (i >> 3) + (i & 7) > q) s[blk][i] = -INFINITY; }
;             }
	v_add_u32_e32 v98, s38, v96
	v_subrev_u32_e32 v99, 63, v98
	v_cmp_le_i32_e32 vcc, v99, v180
	v_cmp_lt_i32_e64 s[8:9], v99, v180
	v_subrev_u32_e32 v99, 61, v98
	v_cndmask_b32_e32 v94, v231, v94, vcc
	v_cmp_le_i32_e32 vcc, v99, v180
	v_subrev_u32_e32 v99, 60, v98
	v_cndmask_b32_e64 v97, v231, v97, s[8:9]
	v_cndmask_b32_e32 v92, v231, v92, vcc
	v_cmp_le_i32_e32 vcc, v99, v180
	v_subrev_u32_e32 v99, 59, v98
	s_nop 0
	v_cndmask_b32_e32 v95, v231, v95, vcc
	v_cmp_le_i32_e32 vcc, v99, v180
	v_subrev_u32_e32 v99, 58, v98
	s_nop 0
	v_cndmask_b32_e32 v90, v231, v90, vcc
	v_cmp_le_i32_e32 vcc, v99, v180
	v_subrev_u32_e32 v99, 57, v98
	s_nop 0
	v_cndmask_b32_e32 v93, v231, v93, vcc
	v_cmp_le_i32_e32 vcc, v99, v180
	v_subrev_u32_e32 v99, 56, v98
	s_nop 0
	v_cndmask_b32_e32 v88, v231, v88, vcc
	v_cmp_le_i32_e32 vcc, v99, v180
	v_subrev_u32_e32 v99, 47, v98
	s_nop 0
	v_cndmask_b32_e32 v91, v231, v91, vcc
	v_cmp_le_i32_e32 vcc, v99, v180
	v_subrev_u32_e32 v99, 46, v98
	s_nop 0
	v_cndmask_b32_e32 v86, v231, v86, vcc
	v_cmp_le_i32_e32 vcc, v99, v180
	v_subrev_u32_e32 v99, 45, v98
	s_nop 0
	v_cndmask_b32_e32 v87, v231, v87, vcc
	v_cmp_le_i32_e32 vcc, v99, v180
	v_subrev_u32_e32 v99, 44, v98
	s_nop 0
	v_cndmask_b32_e32 v84, v231, v84, vcc
	v_cmp_le_i32_e32 vcc, v99, v180
	v_subrev_u32_e32 v99, 43, v98
	s_nop 0
	v_cndmask_b32_e32 v85, v231, v85, vcc
	v_cmp_le_i32_e32 vcc, v99, v180
	v_subrev_u32_e32 v99, 42, v98
	s_nop 0
	v_cndmask_b32_e32 v82, v231, v82, vcc
	v_cmp_le_i32_e32 vcc, v99, v180
	v_subrev_u32_e32 v99, 41, v98
	s_nop 0
	v_cndmask_b32_e32 v83, v231, v83, vcc
	v_cmp_le_i32_e32 vcc, v99, v180
	v_subrev_u32_e32 v99, 40, v98
	s_nop 0
	v_cndmask_b32_e32 v80, v231, v80, vcc
	v_cmp_le_i32_e32 vcc, v99, v180
	v_subrev_u32_e32 v99, 31, v98
	s_nop 0
	v_cndmask_b32_e32 v81, v231, v81, vcc
	v_cmp_le_i32_e32 vcc, v99, v180
	v_subrev_u32_e32 v99, 30, v98
	s_nop 0
	v_cndmask_b32_e32 v0, v231, v0, vcc
	v_cmp_le_i32_e32 vcc, v99, v180
	v_subrev_u32_e32 v99, 29, v98
	s_nop 0
	v_cndmask_b32_e32 v89, v231, v89, vcc
	v_cmp_le_i32_e32 vcc, v99, v180
	v_subrev_u32_e32 v99, 28, v98
	s_nop 0
	v_cndmask_b32_e32 v2, v231, v2, vcc
	v_cmp_le_i32_e32 vcc, v99, v180
	v_subrev_u32_e32 v99, 27, v98
	s_nop 0
	v_cndmask_b32_e32 v3, v231, v3, vcc
	v_cmp_le_i32_e32 vcc, v99, v180
	v_subrev_u32_e32 v99, 26, v98
	s_nop 0
	v_cndmask_b32_e32 v4, v231, v4, vcc
	v_cmp_le_i32_e32 vcc, v99, v180
	v_subrev_u32_e32 v99, 25, v98
	s_nop 0
	v_cndmask_b32_e32 v5, v231, v5, vcc
	v_cmp_le_i32_e32 vcc, v99, v180
	v_subrev_u32_e32 v99, 24, v98
	s_nop 0
	v_cndmask_b32_e32 v6, v231, v6, vcc
	v_cmp_le_i32_e32 vcc, v99, v180
	v_add_u32_e32 v99, -15, v98
	s_nop 0
	v_cndmask_b32_e32 v7, v231, v7, vcc
	v_cmp_le_i32_e32 vcc, v99, v180
	v_add_u32_e32 v99, -14, v98
	s_nop 0
	v_cndmask_b32_e32 v8, v231, v8, vcc
	v_cmp_le_i32_e32 vcc, v99, v180
	v_add_u32_e32 v99, -13, v98
	s_nop 0
	v_cndmask_b32_e32 v9, v231, v9, vcc
	v_cmp_le_i32_e32 vcc, v99, v180
	v_add_u32_e32 v99, -12, v98
	s_nop 0
	v_cndmask_b32_e32 v10, v231, v10, vcc
	v_cmp_le_i32_e32 vcc, v99, v180
	v_add_u32_e32 v99, -11, v98
	s_nop 0
	v_cndmask_b32_e32 v11, v231, v11, vcc
	v_cmp_le_i32_e32 vcc, v99, v180
	v_add_u32_e32 v99, -10, v98
	s_nop 0
	v_cndmask_b32_e32 v12, v231, v12, vcc
	v_cmp_le_i32_e32 vcc, v99, v180
	v_add_u32_e32 v99, -9, v98
	v_add_u32_e32 v98, -8, v98
	v_cndmask_b32_e32 v13, v231, v13, vcc
	v_cmp_le_i32_e32 vcc, v99, v180
	s_nop 1
	v_cndmask_b32_e32 v14, v231, v14, vcc
	v_cmp_le_i32_e32 vcc, v98, v180
	s_nop 1
	v_cndmask_b32_e32 v15, v231, v15, vcc
